# E1 + hoisted ssq loads / counted waits in mlp-in epilogue and in-proj (pn>=3) epilogue
# speedup vs baseline: 1.0065x; 1.0065x over previous
.LBB0_216:
	v_ashrrev_i32_e32 v173, 31, v172
	v_lshl_add_u64 v[132:133], v[172:173], 2, s[46:47]
	global_load_dword v210, v[132:133], off
	global_load_dword v211, v[132:133], off offset:64
	global_load_dword v212, v[132:133], off offset:128
	global_load_dword v213, v[132:133], off offset:192
	global_load_dword v214, v[132:133], off offset:512
	global_load_dword v215, v[132:133], off offset:576
	global_load_dword v216, v[132:133], off offset:640
	global_load_dword v217, v[132:133], off offset:704
	v_lshl_add_u32 v136, s95, 8, v245
	v_mov_b32_e32 v137, v2
	v_mov_b64_e32 v[134:135], s[48:49]
	v_mad_i64_i32 v[140:141], s[24:25], v172, s83, v[134:135]
	v_lshlrev_b64 v[136:137], 1, v[136:137]
	v_lshl_add_u64 v[140:141], v[140:141], 0, v[136:137]
	s_waitcnt vmcnt(7)
	s_nop 1
	v_fmamk_f32 v138, v210, 0x3a800000, v202
	v_rsq_f32_e32 v138, v138
	s_nop 0
	v_pk_mul_f32 v[130:131], v[130:131], v[138:139] op_sel_hi:[1,0]
	v_pk_mul_f32 v[128:129], v[128:129], v[138:139] op_sel_hi:[1,0]
	v_pk_mul_f32 v[126:127], v[126:127], v[138:139] op_sel_hi:[1,0]
	v_pk_mul_f32 v[124:125], v[124:125], v[138:139] op_sel_hi:[1,0]
	v_pk_mul_f32 v[122:123], v[122:123], v[138:139] op_sel_hi:[1,0]
	v_pk_mul_f32 v[120:121], v[120:121], v[138:139] op_sel_hi:[1,0]
	v_pk_mul_f32 v[142:143], v[118:119], v[138:139] op_sel_hi:[1,0]
	v_pk_mul_f32 v[138:139], v[116:117], v[138:139] op_sel_hi:[1,0]
	v_cvt_pk_bf16_f32 v116, v128, v129
	v_cvt_pk_bf16_f32 v117, v130, v131
	v_cvt_pk_bf16_f32 v118, v124, v125
	v_cvt_pk_bf16_f32 v119, v126, v127
	global_store_dwordx4 v[140:141], v[116:119], off
	s_nop 1
	v_cvt_pk_bf16_f32 v116, v120, v121
	v_cvt_pk_bf16_f32 v117, v122, v123
	v_cvt_pk_bf16_f32 v118, v138, v139
	v_cvt_pk_bf16_f32 v119, v142, v143
	global_store_dwordx4 v[140:141], v[116:119], off offset:256
	s_nop 0
	s_nop 0
	v_or_b32_e32 v117, 16, v172
	v_mad_i64_i32 v[118:119], s[24:25], v117, s83, v[134:135]
	v_lshl_add_u64 v[118:119], v[118:119], 0, v[136:137]
	s_waitcnt vmcnt(8)
	s_nop 1
	v_fmamk_f32 v116, v211, 0x3a800000, v202
	v_rsq_f32_e32 v116, v116
	s_nop 0
	v_pk_mul_f32 v[114:115], v[114:115], v[116:117] op_sel_hi:[1,0]
	v_pk_mul_f32 v[112:113], v[112:113], v[116:117] op_sel_hi:[1,0]
	v_pk_mul_f32 v[110:111], v[110:111], v[116:117] op_sel_hi:[1,0]
	v_pk_mul_f32 v[108:109], v[108:109], v[116:117] op_sel_hi:[1,0]
	v_pk_mul_f32 v[106:107], v[106:107], v[116:117] op_sel_hi:[1,0]
	v_pk_mul_f32 v[104:105], v[104:105], v[116:117] op_sel_hi:[1,0]
	v_pk_mul_f32 v[120:121], v[102:103], v[116:117] op_sel_hi:[1,0]
	v_pk_mul_f32 v[116:117], v[100:101], v[116:117] op_sel_hi:[1,0]
	v_cvt_pk_bf16_f32 v100, v112, v113
	v_cvt_pk_bf16_f32 v101, v114, v115
	v_cvt_pk_bf16_f32 v102, v108, v109
	v_cvt_pk_bf16_f32 v103, v110, v111
	global_store_dwordx4 v[118:119], v[100:103], off
	s_nop 1
	v_cvt_pk_bf16_f32 v100, v104, v105
	v_cvt_pk_bf16_f32 v101, v106, v107
	v_cvt_pk_bf16_f32 v102, v116, v117
	v_cvt_pk_bf16_f32 v103, v120, v121
	global_store_dwordx4 v[118:119], v[100:103], off offset:256
	s_nop 0
	s_nop 0
	v_or_b32_e32 v101, 32, v172
	v_mad_i64_i32 v[102:103], s[24:25], v101, s83, v[134:135]
	v_lshl_add_u64 v[102:103], v[102:103], 0, v[136:137]
	s_waitcnt vmcnt(9)
	s_nop 1
	v_fmamk_f32 v100, v212, 0x3a800000, v202
	v_rsq_f32_e32 v100, v100
	s_nop 0
	v_pk_mul_f32 v[98:99], v[98:99], v[100:101] op_sel_hi:[1,0]
	v_pk_mul_f32 v[96:97], v[96:97], v[100:101] op_sel_hi:[1,0]
	v_pk_mul_f32 v[94:95], v[94:95], v[100:101] op_sel_hi:[1,0]
	v_pk_mul_f32 v[92:93], v[92:93], v[100:101] op_sel_hi:[1,0]
	v_pk_mul_f32 v[90:91], v[90:91], v[100:101] op_sel_hi:[1,0]
	v_pk_mul_f32 v[88:89], v[88:89], v[100:101] op_sel_hi:[1,0]
	v_pk_mul_f32 v[104:105], v[86:87], v[100:101] op_sel_hi:[1,0]
	v_pk_mul_f32 v[100:101], v[84:85], v[100:101] op_sel_hi:[1,0]
	v_cvt_pk_bf16_f32 v84, v96, v97
	v_cvt_pk_bf16_f32 v85, v98, v99
	v_cvt_pk_bf16_f32 v86, v92, v93
	v_cvt_pk_bf16_f32 v87, v94, v95
	global_store_dwordx4 v[102:103], v[84:87], off
	s_nop 1
	v_cvt_pk_bf16_f32 v84, v88, v89
	v_cvt_pk_bf16_f32 v85, v90, v91
	v_cvt_pk_bf16_f32 v86, v100, v101
	v_cvt_pk_bf16_f32 v87, v104, v105
	global_store_dwordx4 v[102:103], v[84:87], off offset:256
	s_nop 0
	s_nop 0
	v_or_b32_e32 v85, 48, v172
	v_mad_i64_i32 v[86:87], s[24:25], v85, s83, v[134:135]
	v_lshl_add_u64 v[86:87], v[86:87], 0, v[136:137]
	s_waitcnt vmcnt(10)
	s_nop 1
	v_fmamk_f32 v84, v213, 0x3a800000, v202
	v_rsq_f32_e32 v84, v84
	s_nop 0
	v_pk_mul_f32 v[82:83], v[82:83], v[84:85] op_sel_hi:[1,0]
	v_pk_mul_f32 v[80:81], v[80:81], v[84:85] op_sel_hi:[1,0]
	v_pk_mul_f32 v[78:79], v[78:79], v[84:85] op_sel_hi:[1,0]
	v_pk_mul_f32 v[76:77], v[76:77], v[84:85] op_sel_hi:[1,0]
	v_pk_mul_f32 v[74:75], v[74:75], v[84:85] op_sel_hi:[1,0]
	v_pk_mul_f32 v[72:73], v[72:73], v[84:85] op_sel_hi:[1,0]
	v_pk_mul_f32 v[88:89], v[70:71], v[84:85] op_sel_hi:[1,0]
	v_pk_mul_f32 v[84:85], v[68:69], v[84:85] op_sel_hi:[1,0]
	v_cvt_pk_bf16_f32 v68, v80, v81
	v_cvt_pk_bf16_f32 v69, v82, v83
	v_cvt_pk_bf16_f32 v70, v76, v77
	v_cvt_pk_bf16_f32 v71, v78, v79
	global_store_dwordx4 v[86:87], v[68:71], off
	s_nop 1
	v_cvt_pk_bf16_f32 v68, v72, v73
	v_cvt_pk_bf16_f32 v69, v74, v75
	v_cvt_pk_bf16_f32 v70, v84, v85
	v_cvt_pk_bf16_f32 v71, v88, v89
	global_store_dwordx4 v[86:87], v[68:71], off offset:256
	s_nop 0
	s_nop 0
	v_add_u32_e32 v69, 0x80, v172
	v_mad_i64_i32 v[70:71], s[24:25], v69, s83, v[134:135]
	v_lshl_add_u64 v[70:71], v[70:71], 0, v[136:137]
	s_waitcnt vmcnt(11)
	s_nop 1
	v_fmamk_f32 v68, v214, 0x3a800000, v202
	v_rsq_f32_e32 v68, v68
	s_nop 0
	v_pk_mul_f32 v[66:67], v[66:67], v[68:69] op_sel_hi:[1,0]
	v_pk_mul_f32 v[64:65], v[64:65], v[68:69] op_sel_hi:[1,0]
	v_pk_mul_f32 v[62:63], v[62:63], v[68:69] op_sel_hi:[1,0]
	v_pk_mul_f32 v[60:61], v[60:61], v[68:69] op_sel_hi:[1,0]
	v_pk_mul_f32 v[58:59], v[58:59], v[68:69] op_sel_hi:[1,0]
	v_pk_mul_f32 v[56:57], v[56:57], v[68:69] op_sel_hi:[1,0]
	v_pk_mul_f32 v[72:73], v[54:55], v[68:69] op_sel_hi:[1,0]
	v_pk_mul_f32 v[68:69], v[52:53], v[68:69] op_sel_hi:[1,0]
	v_cvt_pk_bf16_f32 v52, v64, v65
	v_cvt_pk_bf16_f32 v53, v66, v67
	v_cvt_pk_bf16_f32 v54, v60, v61
	v_cvt_pk_bf16_f32 v55, v62, v63
	global_store_dwordx4 v[70:71], v[52:55], off
	s_nop 1
	v_cvt_pk_bf16_f32 v52, v56, v57
	v_cvt_pk_bf16_f32 v53, v58, v59
	v_cvt_pk_bf16_f32 v54, v68, v69
	v_cvt_pk_bf16_f32 v55, v72, v73
	global_store_dwordx4 v[70:71], v[52:55], off offset:256
	s_nop 0
	s_nop 0
	v_add_u32_e32 v53, 0x90, v172
	v_mad_i64_i32 v[54:55], s[24:25], v53, s83, v[134:135]
	v_lshl_add_u64 v[54:55], v[54:55], 0, v[136:137]
	s_waitcnt vmcnt(12)
	s_nop 1
	v_fmamk_f32 v52, v215, 0x3a800000, v202
	v_rsq_f32_e32 v52, v52
	s_nop 0
	v_pk_mul_f32 v[50:51], v[50:51], v[52:53] op_sel_hi:[1,0]
	v_pk_mul_f32 v[48:49], v[48:49], v[52:53] op_sel_hi:[1,0]
	v_pk_mul_f32 v[46:47], v[46:47], v[52:53] op_sel_hi:[1,0]
	v_pk_mul_f32 v[44:45], v[44:45], v[52:53] op_sel_hi:[1,0]
	v_pk_mul_f32 v[42:43], v[42:43], v[52:53] op_sel_hi:[1,0]
	v_pk_mul_f32 v[40:41], v[40:41], v[52:53] op_sel_hi:[1,0]
	v_pk_mul_f32 v[56:57], v[38:39], v[52:53] op_sel_hi:[1,0]
	v_pk_mul_f32 v[52:53], v[36:37], v[52:53] op_sel_hi:[1,0]
	v_cvt_pk_bf16_f32 v36, v48, v49
	v_cvt_pk_bf16_f32 v37, v50, v51
	v_cvt_pk_bf16_f32 v38, v44, v45
	v_cvt_pk_bf16_f32 v39, v46, v47
	global_store_dwordx4 v[54:55], v[36:39], off
	s_nop 1
	v_cvt_pk_bf16_f32 v36, v40, v41
	v_cvt_pk_bf16_f32 v37, v42, v43
	v_cvt_pk_bf16_f32 v38, v52, v53
	v_cvt_pk_bf16_f32 v39, v56, v57
	global_store_dwordx4 v[54:55], v[36:39], off offset:256
	s_nop 0
	s_nop 0
	v_add_u32_e32 v37, 0xa0, v172
	v_mad_i64_i32 v[38:39], s[24:25], v37, s83, v[134:135]
	v_lshl_add_u64 v[38:39], v[38:39], 0, v[136:137]
	s_waitcnt vmcnt(13)
	s_nop 1
	v_fmamk_f32 v36, v216, 0x3a800000, v202
	v_rsq_f32_e32 v36, v36
	s_nop 0
	v_pk_mul_f32 v[34:35], v[34:35], v[36:37] op_sel_hi:[1,0]
	v_pk_mul_f32 v[32:33], v[32:33], v[36:37] op_sel_hi:[1,0]
	v_pk_mul_f32 v[30:31], v[30:31], v[36:37] op_sel_hi:[1,0]
	v_pk_mul_f32 v[28:29], v[28:29], v[36:37] op_sel_hi:[1,0]
	v_pk_mul_f32 v[26:27], v[26:27], v[36:37] op_sel_hi:[1,0]
	v_pk_mul_f32 v[24:25], v[24:25], v[36:37] op_sel_hi:[1,0]
	v_pk_mul_f32 v[40:41], v[22:23], v[36:37] op_sel_hi:[1,0]
	v_pk_mul_f32 v[36:37], v[20:21], v[36:37] op_sel_hi:[1,0]
	v_cvt_pk_bf16_f32 v20, v32, v33
	v_cvt_pk_bf16_f32 v21, v34, v35
	v_cvt_pk_bf16_f32 v22, v28, v29
	v_cvt_pk_bf16_f32 v23, v30, v31
	global_store_dwordx4 v[38:39], v[20:23], off
	s_nop 1
	v_cvt_pk_bf16_f32 v20, v24, v25
	v_cvt_pk_bf16_f32 v21, v26, v27
	v_cvt_pk_bf16_f32 v22, v36, v37
	v_cvt_pk_bf16_f32 v23, v40, v41
	global_store_dwordx4 v[38:39], v[20:23], off offset:256
	s_nop 0
	s_nop 0
	v_add_u32_e32 v21, 0xb0, v172
	v_mad_i64_i32 v[22:23], s[24:25], v21, s83, v[134:135]
	v_lshl_add_u64 v[22:23], v[22:23], 0, v[136:137]
	s_waitcnt vmcnt(14)
	s_nop 1
	v_fmamk_f32 v20, v217, 0x3a800000, v202
	v_rsq_f32_e32 v20, v20
	s_nop 0
	v_pk_mul_f32 v[18:19], v[18:19], v[20:21] op_sel_hi:[1,0]
	v_pk_mul_f32 v[16:17], v[16:17], v[20:21] op_sel_hi:[1,0]
	v_pk_mul_f32 v[14:15], v[14:15], v[20:21] op_sel_hi:[1,0]
	v_pk_mul_f32 v[12:13], v[12:13], v[20:21] op_sel_hi:[1,0]
	v_pk_mul_f32 v[10:11], v[10:11], v[20:21] op_sel_hi:[1,0]
	v_pk_mul_f32 v[8:9], v[8:9], v[20:21] op_sel_hi:[1,0]
	v_pk_mul_f32 v[24:25], v[6:7], v[20:21] op_sel_hi:[1,0]
	v_pk_mul_f32 v[20:21], v[4:5], v[20:21] op_sel_hi:[1,0]
	v_cvt_pk_bf16_f32 v4, v16, v17
	v_cvt_pk_bf16_f32 v5, v18, v19
	v_cvt_pk_bf16_f32 v6, v12, v13
	v_cvt_pk_bf16_f32 v7, v14, v15
	global_store_dwordx4 v[22:23], v[4:7], off
	s_nop 1
	v_cvt_pk_bf16_f32 v4, v8, v9
	v_cvt_pk_bf16_f32 v5, v10, v11
	v_cvt_pk_bf16_f32 v6, v20, v21
	v_cvt_pk_bf16_f32 v7, v24, v25
	global_store_dwordx4 v[22:23], v[4:7], off offset:256
	s_andn2_b64 vcc, exec, s[38:39]
	s_mov_b64 s[24:25], -1
	s_cbranch_vccnz .LBB0_180

.LBB0_892:
	v_lshl_add_u32 v144, s71, 8, v3
	v_ashrrev_i32_e32 v145, 31, v144
	v_lshl_add_u64 v[140:141], v[144:145], 2, s[44:45]
	global_load_dword v246, v[140:141], off
	global_load_dword v247, v[140:141], off offset:64
	global_load_dword v248, v[140:141], off offset:128
	global_load_dword v249, v[140:141], off offset:192
	global_load_dword v250, v[140:141], off offset:512
	global_load_dword v251, v[140:141], off offset:576
	global_load_dword v252, v[140:141], off offset:640
	global_load_dword v253, v[140:141], off offset:704
	v_lshl_or_b32 v138, s70, 8, v147
	v_ashrrev_i32_e32 v139, 31, v138
	s_mov_b64 s[24:25], 0x100000
	s_mov_b64 s[28:29], -1
	s_waitcnt vmcnt(7)
	s_nop 1
	v_fmamk_f32 v142, v246, 0x3a800000, v202
	v_rsq_f32_e32 v150, v142
	v_lshlrev_b64 v[142:143], 13, v[144:145]
	v_lshl_add_u64 v[152:153], s[46:47], 0, v[142:143]
	v_lshlrev_b64 v[142:143], 1, v[138:139]
	v_pk_mul_f32 v[124:125], v[124:125], v[150:151] op_sel_hi:[1,0]
	v_pk_mul_f32 v[128:129], v[128:129], v[150:151] op_sel_hi:[1,0]
	v_pk_mul_f32 v[126:127], v[126:127], v[150:151] op_sel_hi:[1,0]
	v_max_f32_e32 v124, 0, v124
	v_pk_mul_f32 v[130:131], v[130:131], v[150:151] op_sel_hi:[1,0]
	v_mul_f32_e32 v145, v124, v124
	v_max_f32_e32 v124, 0, v129
	v_max_f32_e32 v125, 0, v125
	v_max_f32_e32 v126, 0, v126
	v_max_f32_e32 v128, 0, v128
	v_mul_f32_e32 v124, v124, v124
	v_mul_f32_e32 v129, v125, v125
	v_max_f32_e32 v125, 0, v130
	v_mul_f32_e32 v130, v126, v126
	v_max_f32_e32 v126, 0, v131
	v_max_f32_e32 v127, 0, v127
	v_pk_mul_f32 v[116:117], v[116:117], v[150:151] op_sel_hi:[1,0]
	v_lshl_add_u64 v[138:139], v[152:153], 0, v[142:143]
	v_mul_f32_e32 v128, v128, v128
	v_mul_f32_e32 v125, v125, v125
	v_mul_f32_e32 v126, v126, v126
	v_mul_f32_e32 v127, v127, v127
	v_cvt_pk_bf16_f32 v124, v128, v124
	v_pk_mul_f32 v[120:121], v[120:121], v[150:151] op_sel_hi:[1,0]
	v_pk_mul_f32 v[118:119], v[118:119], v[150:151] op_sel_hi:[1,0]
	v_max_f32_e32 v116, 0, v116
	v_cvt_pk_bf16_f32 v125, v125, v126
	v_cvt_pk_bf16_f32 v126, v145, v129
	v_cvt_pk_bf16_f32 v127, v130, v127
	global_store_dwordx4 v[138:139], v[124:127], off
	v_pk_mul_f32 v[122:123], v[122:123], v[150:151] op_sel_hi:[1,0]
	v_max_f32_e32 v117, 0, v117
	v_mul_f32_e32 v124, v116, v116
	v_max_f32_e32 v116, 0, v121
	v_max_f32_e32 v118, 0, v118
	v_max_f32_e32 v120, 0, v120
	v_mul_f32_e32 v116, v116, v116
	v_mul_f32_e32 v121, v117, v117
	v_max_f32_e32 v117, 0, v122
	v_mul_f32_e32 v122, v118, v118
	v_max_f32_e32 v118, 0, v123
	v_max_f32_e32 v119, 0, v119
	v_mul_f32_e32 v120, v120, v120
	v_mul_f32_e32 v117, v117, v117
	v_mul_f32_e32 v118, v118, v118
	v_mul_f32_e32 v119, v119, v119
	v_cvt_pk_bf16_f32 v116, v120, v116
	v_cvt_pk_bf16_f32 v117, v117, v118
	v_cvt_pk_bf16_f32 v118, v124, v121
	v_cvt_pk_bf16_f32 v119, v122, v119
	global_store_dwordx4 v[138:139], v[116:119], off offset:256
	s_nop 1
	v_or_b32_e32 v116, 16, v144
	v_ashrrev_i32_e32 v117, 31, v116
	s_nop 0
	v_lshlrev_b64 v[116:117], 13, v[116:117]
	v_lshl_add_u64 v[116:117], s[46:47], 0, v[116:117]
	v_lshl_add_u64 v[116:117], v[116:117], 0, v[142:143]
	s_waitcnt vmcnt(8)
	s_nop 1
	v_fmamk_f32 v118, v247, 0x3a800000, v202
	v_rsq_f32_e32 v118, v118
	s_nop 0
	v_pk_mul_f32 v[108:109], v[108:109], v[118:119] op_sel_hi:[1,0]
	v_pk_mul_f32 v[112:113], v[112:113], v[118:119] op_sel_hi:[1,0]
	v_pk_mul_f32 v[110:111], v[110:111], v[118:119] op_sel_hi:[1,0]
	v_max_f32_e32 v108, 0, v108
	v_pk_mul_f32 v[114:115], v[114:115], v[118:119] op_sel_hi:[1,0]
	v_mul_f32_e32 v119, v108, v108
	v_max_f32_e32 v108, 0, v113
	v_max_f32_e32 v109, 0, v109
	v_max_f32_e32 v110, 0, v110
	v_max_f32_e32 v112, 0, v112
	v_mul_f32_e32 v108, v108, v108
	v_mul_f32_e32 v113, v109, v109
	v_max_f32_e32 v109, 0, v114
	v_mul_f32_e32 v114, v110, v110
	v_max_f32_e32 v110, 0, v115
	v_max_f32_e32 v111, 0, v111
	v_pk_mul_f32 v[100:101], v[100:101], v[118:119] op_sel_hi:[1,0]
	v_mul_f32_e32 v112, v112, v112
	v_mul_f32_e32 v109, v109, v109
	v_mul_f32_e32 v110, v110, v110
	v_mul_f32_e32 v111, v111, v111
	v_cvt_pk_bf16_f32 v108, v112, v108
	v_pk_mul_f32 v[104:105], v[104:105], v[118:119] op_sel_hi:[1,0]
	v_pk_mul_f32 v[102:103], v[102:103], v[118:119] op_sel_hi:[1,0]
	v_max_f32_e32 v100, 0, v100
	v_cvt_pk_bf16_f32 v109, v109, v110
	v_cvt_pk_bf16_f32 v110, v119, v113
	v_cvt_pk_bf16_f32 v111, v114, v111
	global_store_dwordx4 v[116:117], v[108:111], off
	v_pk_mul_f32 v[106:107], v[106:107], v[118:119] op_sel_hi:[1,0]
	v_max_f32_e32 v101, 0, v101
	v_mul_f32_e32 v108, v100, v100
	v_max_f32_e32 v100, 0, v105
	v_max_f32_e32 v102, 0, v102
	v_max_f32_e32 v104, 0, v104
	v_mul_f32_e32 v100, v100, v100
	v_mul_f32_e32 v105, v101, v101
	v_max_f32_e32 v101, 0, v106
	v_mul_f32_e32 v106, v102, v102
	v_max_f32_e32 v102, 0, v107
	v_max_f32_e32 v103, 0, v103
	v_mul_f32_e32 v104, v104, v104
	v_mul_f32_e32 v101, v101, v101
	v_mul_f32_e32 v102, v102, v102
	v_mul_f32_e32 v103, v103, v103
	v_cvt_pk_bf16_f32 v100, v104, v100
	v_cvt_pk_bf16_f32 v101, v101, v102
	v_cvt_pk_bf16_f32 v102, v108, v105
	v_cvt_pk_bf16_f32 v103, v106, v103
	global_store_dwordx4 v[116:117], v[100:103], off offset:256
	s_nop 1
	v_or_b32_e32 v100, 32, v144
	v_ashrrev_i32_e32 v101, 31, v100
	s_nop 0
	v_lshlrev_b64 v[100:101], 13, v[100:101]
	v_lshl_add_u64 v[100:101], s[46:47], 0, v[100:101]
	v_lshl_add_u64 v[100:101], v[100:101], 0, v[142:143]
	s_waitcnt vmcnt(9)
	s_nop 1
	v_fmamk_f32 v102, v248, 0x3a800000, v202
	v_rsq_f32_e32 v102, v102
	s_nop 0
	v_pk_mul_f32 v[92:93], v[92:93], v[102:103] op_sel_hi:[1,0]
	v_pk_mul_f32 v[96:97], v[96:97], v[102:103] op_sel_hi:[1,0]
	v_pk_mul_f32 v[94:95], v[94:95], v[102:103] op_sel_hi:[1,0]
	v_max_f32_e32 v92, 0, v92
	v_pk_mul_f32 v[98:99], v[98:99], v[102:103] op_sel_hi:[1,0]
	v_mul_f32_e32 v103, v92, v92
	v_max_f32_e32 v92, 0, v97
	v_max_f32_e32 v93, 0, v93
	v_max_f32_e32 v94, 0, v94
	v_max_f32_e32 v96, 0, v96
	v_mul_f32_e32 v92, v92, v92
	v_mul_f32_e32 v97, v93, v93
	v_max_f32_e32 v93, 0, v98
	v_mul_f32_e32 v98, v94, v94
	v_max_f32_e32 v94, 0, v99
	v_max_f32_e32 v95, 0, v95
	v_pk_mul_f32 v[84:85], v[84:85], v[102:103] op_sel_hi:[1,0]
	v_mul_f32_e32 v96, v96, v96
	v_mul_f32_e32 v93, v93, v93
	v_mul_f32_e32 v94, v94, v94
	v_mul_f32_e32 v95, v95, v95
	v_cvt_pk_bf16_f32 v92, v96, v92
	v_pk_mul_f32 v[88:89], v[88:89], v[102:103] op_sel_hi:[1,0]
	v_pk_mul_f32 v[86:87], v[86:87], v[102:103] op_sel_hi:[1,0]
	v_max_f32_e32 v84, 0, v84
	v_cvt_pk_bf16_f32 v93, v93, v94
	v_cvt_pk_bf16_f32 v94, v103, v97
	v_cvt_pk_bf16_f32 v95, v98, v95
	global_store_dwordx4 v[100:101], v[92:95], off
	v_pk_mul_f32 v[90:91], v[90:91], v[102:103] op_sel_hi:[1,0]
	v_max_f32_e32 v85, 0, v85
	v_mul_f32_e32 v92, v84, v84
	v_max_f32_e32 v84, 0, v89
	v_max_f32_e32 v86, 0, v86
	v_max_f32_e32 v88, 0, v88
	v_mul_f32_e32 v84, v84, v84
	v_mul_f32_e32 v89, v85, v85
	v_max_f32_e32 v85, 0, v90
	v_mul_f32_e32 v90, v86, v86
	v_max_f32_e32 v86, 0, v91
	v_max_f32_e32 v87, 0, v87
	v_mul_f32_e32 v88, v88, v88
	v_mul_f32_e32 v85, v85, v85
	v_mul_f32_e32 v86, v86, v86
	v_mul_f32_e32 v87, v87, v87
	v_cvt_pk_bf16_f32 v84, v88, v84
	v_cvt_pk_bf16_f32 v85, v85, v86
	v_cvt_pk_bf16_f32 v86, v92, v89
	v_cvt_pk_bf16_f32 v87, v90, v87
	global_store_dwordx4 v[100:101], v[84:87], off offset:256
	s_nop 1
	v_or_b32_e32 v84, 48, v144
	v_ashrrev_i32_e32 v85, 31, v84
	s_nop 0
	v_lshlrev_b64 v[84:85], 13, v[84:85]
	v_lshl_add_u64 v[84:85], s[46:47], 0, v[84:85]
	v_lshl_add_u64 v[84:85], v[84:85], 0, v[142:143]
	s_waitcnt vmcnt(10)
	s_nop 1
	v_fmamk_f32 v86, v249, 0x3a800000, v202
	v_rsq_f32_e32 v86, v86
	s_nop 0
	v_pk_mul_f32 v[76:77], v[76:77], v[86:87] op_sel_hi:[1,0]
	v_pk_mul_f32 v[80:81], v[80:81], v[86:87] op_sel_hi:[1,0]
	v_pk_mul_f32 v[78:79], v[78:79], v[86:87] op_sel_hi:[1,0]
	v_max_f32_e32 v76, 0, v76
	v_pk_mul_f32 v[82:83], v[82:83], v[86:87] op_sel_hi:[1,0]
	v_mul_f32_e32 v87, v76, v76
	v_max_f32_e32 v76, 0, v81
	v_max_f32_e32 v77, 0, v77
	v_max_f32_e32 v78, 0, v78
	v_max_f32_e32 v80, 0, v80
	v_mul_f32_e32 v76, v76, v76
	v_mul_f32_e32 v81, v77, v77
	v_max_f32_e32 v77, 0, v82
	v_mul_f32_e32 v82, v78, v78
	v_max_f32_e32 v78, 0, v83
	v_max_f32_e32 v79, 0, v79
	v_pk_mul_f32 v[70:71], v[70:71], v[86:87] op_sel_hi:[1,0]
	v_pk_mul_f32 v[68:69], v[68:69], v[86:87] op_sel_hi:[1,0]
	v_mul_f32_e32 v80, v80, v80
	v_mul_f32_e32 v77, v77, v77
	v_mul_f32_e32 v78, v78, v78
	v_mul_f32_e32 v79, v79, v79
	v_cvt_pk_bf16_f32 v76, v80, v76
	v_pk_mul_f32 v[74:75], v[74:75], v[86:87] op_sel_hi:[1,0]
	v_pk_mul_f32 v[72:73], v[72:73], v[86:87] op_sel_hi:[1,0]
	v_max_f32_e32 v68, 0, v68
	v_max_f32_e32 v69, 0, v69
	v_max_f32_e32 v70, 0, v70
	v_cvt_pk_bf16_f32 v77, v77, v78
	v_cvt_pk_bf16_f32 v78, v87, v81
	v_cvt_pk_bf16_f32 v79, v82, v79
	global_store_dwordx4 v[84:85], v[76:79], off
	v_max_f32_e32 v71, 0, v71
	v_max_f32_e32 v72, 0, v72
	v_mul_f32_e32 v76, v68, v68
	v_max_f32_e32 v68, 0, v73
	v_mul_f32_e32 v73, v69, v69
	v_max_f32_e32 v69, 0, v74
	v_mul_f32_e32 v74, v70, v70
	v_max_f32_e32 v70, 0, v75
	v_mul_f32_e32 v68, v68, v68
	v_mul_f32_e32 v69, v69, v69
	v_mul_f32_e32 v70, v70, v70
	v_mul_f32_e32 v71, v71, v71
	v_mul_f32_e32 v72, v72, v72
	v_cvt_pk_bf16_f32 v68, v72, v68
	v_cvt_pk_bf16_f32 v69, v69, v70
	v_cvt_pk_bf16_f32 v70, v76, v73
	v_cvt_pk_bf16_f32 v71, v74, v71
	global_store_dwordx4 v[84:85], v[68:71], off offset:256
	s_nop 0
	s_waitcnt vmcnt(11)
	s_nop 1
	v_fmamk_f32 v68, v250, 0x3a800000, v202
	v_rsq_f32_e32 v70, v68
	v_lshl_add_u64 v[68:69], v[138:139], 0, s[24:25]
	s_mov_b32 s24, 0x100000
	v_pk_mul_f32 v[60:61], v[60:61], v[70:71] op_sel_hi:[1,0]
	v_pk_mul_f32 v[64:65], v[64:65], v[70:71] op_sel_hi:[1,0]
	v_pk_mul_f32 v[62:63], v[62:63], v[70:71] op_sel_hi:[1,0]
	v_max_f32_e32 v60, 0, v60
	v_pk_mul_f32 v[66:67], v[66:67], v[70:71] op_sel_hi:[1,0]
	v_max_f32_e32 v64, 0, v64
	v_mul_f32_e32 v71, v60, v60
	v_max_f32_e32 v60, 0, v65
	v_max_f32_e32 v61, 0, v61
	v_max_f32_e32 v62, 0, v62
	v_mul_f32_e32 v64, v64, v64
	v_mul_f32_e32 v60, v60, v60
	v_mul_f32_e32 v65, v61, v61
	v_max_f32_e32 v61, 0, v66
	v_mul_f32_e32 v66, v62, v62
	v_max_f32_e32 v62, 0, v67
	v_mul_f32_e32 v61, v61, v61
	v_max_f32_e32 v63, 0, v63
	v_mul_f32_e32 v62, v62, v62
	v_cvt_pk_bf16_f32 v60, v64, v60
	v_add_co_u32_e32 v64, vcc, s24, v138
	v_pk_mul_f32 v[54:55], v[54:55], v[70:71] op_sel_hi:[1,0]
	v_pk_mul_f32 v[52:53], v[52:53], v[70:71] op_sel_hi:[1,0]
	v_mul_f32_e32 v63, v63, v63
	v_cvt_pk_bf16_f32 v61, v61, v62
	v_cvt_pk_bf16_f32 v62, v71, v65
	v_addc_co_u32_e32 v65, vcc, 0, v139, vcc
	v_pk_mul_f32 v[58:59], v[58:59], v[70:71] op_sel_hi:[1,0]
	v_pk_mul_f32 v[56:57], v[56:57], v[70:71] op_sel_hi:[1,0]
	v_max_f32_e32 v52, 0, v52
	v_max_f32_e32 v53, 0, v53
	v_max_f32_e32 v54, 0, v54
	v_cvt_pk_bf16_f32 v63, v66, v63
	global_store_dwordx4 v[64:65], v[60:63], off
	v_max_f32_e32 v55, 0, v55
	v_max_f32_e32 v56, 0, v56
	v_mul_f32_e32 v60, v52, v52
	v_max_f32_e32 v52, 0, v57
	v_mul_f32_e32 v57, v53, v53
	v_max_f32_e32 v53, 0, v58
	v_mul_f32_e32 v58, v54, v54
	v_max_f32_e32 v54, 0, v59
	v_mul_f32_e32 v52, v52, v52
	v_mul_f32_e32 v53, v53, v53
	v_mul_f32_e32 v54, v54, v54
	v_mul_f32_e32 v55, v55, v55
	v_mul_f32_e32 v56, v56, v56
	v_cvt_pk_bf16_f32 v52, v56, v52
	v_cvt_pk_bf16_f32 v53, v53, v54
	v_cvt_pk_bf16_f32 v54, v60, v57
	v_cvt_pk_bf16_f32 v55, v58, v55
	global_store_dwordx4 v[68:69], v[52:55], off offset:256
	s_nop 0
	s_mov_b64 s[24:25], 0x120000
	s_waitcnt vmcnt(12)
	s_nop 1
	v_fmamk_f32 v52, v251, 0x3a800000, v202
	v_rsq_f32_e32 v54, v52
	v_lshl_add_u64 v[52:53], v[138:139], 0, s[24:25]
	s_mov_b32 s24, 0x120000
	v_pk_mul_f32 v[44:45], v[44:45], v[54:55] op_sel_hi:[1,0]
	v_pk_mul_f32 v[48:49], v[48:49], v[54:55] op_sel_hi:[1,0]
	v_pk_mul_f32 v[46:47], v[46:47], v[54:55] op_sel_hi:[1,0]
	v_max_f32_e32 v44, 0, v44
	v_pk_mul_f32 v[50:51], v[50:51], v[54:55] op_sel_hi:[1,0]
	v_max_f32_e32 v48, 0, v48
	v_mul_f32_e32 v55, v44, v44
	v_max_f32_e32 v44, 0, v49
	v_max_f32_e32 v45, 0, v45
	v_max_f32_e32 v46, 0, v46
	v_mul_f32_e32 v48, v48, v48
	v_mul_f32_e32 v44, v44, v44
	v_mul_f32_e32 v49, v45, v45
	v_max_f32_e32 v45, 0, v50
	v_mul_f32_e32 v50, v46, v46
	v_max_f32_e32 v46, 0, v51
	v_mul_f32_e32 v45, v45, v45
	v_max_f32_e32 v47, 0, v47
	v_mul_f32_e32 v46, v46, v46
	v_cvt_pk_bf16_f32 v44, v48, v44
	v_add_co_u32_e32 v48, vcc, s24, v138
	v_pk_mul_f32 v[38:39], v[38:39], v[54:55] op_sel_hi:[1,0]
	v_pk_mul_f32 v[36:37], v[36:37], v[54:55] op_sel_hi:[1,0]
	v_mul_f32_e32 v47, v47, v47
	v_cvt_pk_bf16_f32 v45, v45, v46
	v_cvt_pk_bf16_f32 v46, v55, v49
	v_addc_co_u32_e32 v49, vcc, 0, v139, vcc
	v_pk_mul_f32 v[42:43], v[42:43], v[54:55] op_sel_hi:[1,0]
	v_pk_mul_f32 v[40:41], v[40:41], v[54:55] op_sel_hi:[1,0]
	v_max_f32_e32 v36, 0, v36
	v_max_f32_e32 v37, 0, v37
	v_max_f32_e32 v38, 0, v38
	v_cvt_pk_bf16_f32 v47, v50, v47
	global_store_dwordx4 v[48:49], v[44:47], off
	v_max_f32_e32 v39, 0, v39
	v_max_f32_e32 v40, 0, v40
	v_mul_f32_e32 v44, v36, v36
	v_max_f32_e32 v36, 0, v41
	v_mul_f32_e32 v41, v37, v37
	v_max_f32_e32 v37, 0, v42
	v_mul_f32_e32 v42, v38, v38
	v_max_f32_e32 v38, 0, v43
	v_mul_f32_e32 v36, v36, v36
	v_mul_f32_e32 v37, v37, v37
	v_mul_f32_e32 v38, v38, v38
	v_mul_f32_e32 v39, v39, v39
	v_mul_f32_e32 v40, v40, v40
	v_cvt_pk_bf16_f32 v36, v40, v36
	v_cvt_pk_bf16_f32 v37, v37, v38
	v_cvt_pk_bf16_f32 v38, v44, v41
	v_cvt_pk_bf16_f32 v39, v42, v39
	global_store_dwordx4 v[52:53], v[36:39], off offset:256
	s_nop 0
	s_mov_b64 s[24:25], 0x140000
	s_waitcnt vmcnt(13)
	s_nop 1
	v_fmamk_f32 v36, v252, 0x3a800000, v202
	v_rsq_f32_e32 v38, v36
	v_lshl_add_u64 v[36:37], v[138:139], 0, s[24:25]
	s_mov_b32 s24, 0x140000
	v_pk_mul_f32 v[28:29], v[28:29], v[38:39] op_sel_hi:[1,0]
	v_pk_mul_f32 v[32:33], v[32:33], v[38:39] op_sel_hi:[1,0]
	v_pk_mul_f32 v[30:31], v[30:31], v[38:39] op_sel_hi:[1,0]
	v_max_f32_e32 v28, 0, v28
	v_pk_mul_f32 v[34:35], v[34:35], v[38:39] op_sel_hi:[1,0]
	v_max_f32_e32 v32, 0, v32
	v_mul_f32_e32 v39, v28, v28
	v_max_f32_e32 v28, 0, v33
	v_max_f32_e32 v29, 0, v29
	v_max_f32_e32 v30, 0, v30
	v_mul_f32_e32 v32, v32, v32
	v_mul_f32_e32 v28, v28, v28
	v_mul_f32_e32 v33, v29, v29
	v_max_f32_e32 v29, 0, v34
	v_mul_f32_e32 v34, v30, v30
	v_max_f32_e32 v30, 0, v35
	v_mul_f32_e32 v29, v29, v29
	v_max_f32_e32 v31, 0, v31
	v_mul_f32_e32 v30, v30, v30
	v_cvt_pk_bf16_f32 v28, v32, v28
	v_add_co_u32_e32 v32, vcc, s24, v138
	v_pk_mul_f32 v[22:23], v[22:23], v[38:39] op_sel_hi:[1,0]
	v_pk_mul_f32 v[20:21], v[20:21], v[38:39] op_sel_hi:[1,0]
	v_mul_f32_e32 v31, v31, v31
	v_cvt_pk_bf16_f32 v29, v29, v30
	v_cvt_pk_bf16_f32 v30, v39, v33
	v_addc_co_u32_e32 v33, vcc, 0, v139, vcc
	v_pk_mul_f32 v[26:27], v[26:27], v[38:39] op_sel_hi:[1,0]
	v_pk_mul_f32 v[24:25], v[24:25], v[38:39] op_sel_hi:[1,0]
	v_max_f32_e32 v20, 0, v20
	v_max_f32_e32 v21, 0, v21
	v_max_f32_e32 v22, 0, v22
	v_cvt_pk_bf16_f32 v31, v34, v31
	global_store_dwordx4 v[32:33], v[28:31], off
	v_max_f32_e32 v23, 0, v23
	v_max_f32_e32 v24, 0, v24
	v_mul_f32_e32 v28, v20, v20
	v_max_f32_e32 v20, 0, v25
	v_mul_f32_e32 v25, v21, v21
	v_max_f32_e32 v21, 0, v26
	v_mul_f32_e32 v26, v22, v22
	v_max_f32_e32 v22, 0, v27
	v_mul_f32_e32 v20, v20, v20
	v_mul_f32_e32 v21, v21, v21
	v_mul_f32_e32 v22, v22, v22
	v_mul_f32_e32 v23, v23, v23
	v_mul_f32_e32 v24, v24, v24
	v_cvt_pk_bf16_f32 v20, v24, v20
	v_cvt_pk_bf16_f32 v21, v21, v22
	v_cvt_pk_bf16_f32 v22, v28, v25
	v_cvt_pk_bf16_f32 v23, v26, v23
	global_store_dwordx4 v[36:37], v[20:23], off offset:256
	s_nop 0
	s_mov_b64 s[24:25], 0x160000
	v_lshl_add_u64 v[22:23], v[138:139], 0, s[24:25]
	s_mov_b32 s24, 0x160000
	s_waitcnt vmcnt(14)
	s_nop 1
	v_fmamk_f32 v20, v253, 0x3a800000, v202
	v_rsq_f32_e32 v20, v20
	s_nop 0
	v_pk_mul_f32 v[12:13], v[12:13], v[20:21] op_sel_hi:[1,0]
	v_pk_mul_f32 v[16:17], v[16:17], v[20:21] op_sel_hi:[1,0]
	v_pk_mul_f32 v[14:15], v[14:15], v[20:21] op_sel_hi:[1,0]
	v_max_f32_e32 v12, 0, v12
	v_pk_mul_f32 v[18:19], v[18:19], v[20:21] op_sel_hi:[1,0]
	v_max_f32_e32 v16, 0, v16
	v_mul_f32_e32 v21, v12, v12
	v_max_f32_e32 v12, 0, v17
	v_max_f32_e32 v13, 0, v13
	v_max_f32_e32 v14, 0, v14
	v_mul_f32_e32 v16, v16, v16
	v_mul_f32_e32 v12, v12, v12
	v_mul_f32_e32 v17, v13, v13
	v_max_f32_e32 v13, 0, v18
	v_mul_f32_e32 v18, v14, v14
	v_max_f32_e32 v14, 0, v19
	v_mul_f32_e32 v13, v13, v13
	v_max_f32_e32 v15, 0, v15
	v_mul_f32_e32 v14, v14, v14
	v_cvt_pk_bf16_f32 v12, v16, v12
	v_add_co_u32_e32 v16, vcc, s24, v138
	v_pk_mul_f32 v[6:7], v[6:7], v[20:21] op_sel_hi:[1,0]
	v_pk_mul_f32 v[4:5], v[4:5], v[20:21] op_sel_hi:[1,0]
	v_mul_f32_e32 v15, v15, v15
	v_cvt_pk_bf16_f32 v13, v13, v14
	v_cvt_pk_bf16_f32 v14, v21, v17
	v_addc_co_u32_e32 v17, vcc, 0, v139, vcc
	v_pk_mul_f32 v[10:11], v[10:11], v[20:21] op_sel_hi:[1,0]
	v_pk_mul_f32 v[8:9], v[8:9], v[20:21] op_sel_hi:[1,0]
	v_max_f32_e32 v4, 0, v4
	v_max_f32_e32 v5, 0, v5
	v_max_f32_e32 v6, 0, v6
	v_cvt_pk_bf16_f32 v15, v18, v15
	global_store_dwordx4 v[16:17], v[12:15], off
	v_max_f32_e32 v7, 0, v7
	v_max_f32_e32 v8, 0, v8
	v_mul_f32_e32 v12, v4, v4
	v_max_f32_e32 v4, 0, v9
	v_mul_f32_e32 v9, v5, v5
	v_max_f32_e32 v5, 0, v10
	v_mul_f32_e32 v10, v6, v6
	v_max_f32_e32 v6, 0, v11
	v_mul_f32_e32 v4, v4, v4
	v_mul_f32_e32 v5, v5, v5
	v_mul_f32_e32 v6, v6, v6
	v_mul_f32_e32 v7, v7, v7
	s_andn2_b64 vcc, exec, s[40:41]
	v_mul_f32_e32 v8, v8, v8
	v_cvt_pk_bf16_f32 v4, v8, v4
	v_cvt_pk_bf16_f32 v5, v5, v6
	v_cvt_pk_bf16_f32 v6, v12, v9
	v_cvt_pk_bf16_f32 v7, v10, v7
	global_store_dwordx4 v[22:23], v[4:7], off offset:256
	s_cbranch_vccnz .LBB0_881
	s_andn2_b64 vcc, exec, s[42:43]
	s_cbranch_vccnz .LBB0_880
	s_barrier
	s_branch .LBB0_880
